# pooling item MFMA part: weight fragments and the four per-channel scale quads loaded up front (eight round trips become two)
# speedup vs baseline: 1.0007x; 1.0007x over previous
.LBB0_674:
	s_or_b64 exec, exec, s[4:5]
	v_bfe_u32 v52, v0, 4, 2
	v_and_b32_e32 v6, 0xffffffcf, v0
	v_readlane_b32 s4, v255, 43
	v_lshl_add_u32 v2, v0, 1, 0
	v_lshlrev_b32_e32 v16, 4, v52
	v_readlane_b32 s5, v255, 44
	v_ashrrev_i32_e32 v7, 31, v6
	ds_write_b16 v2, v1 offset:65520
	v_lshl_add_u64 v[22:23], s[4:5], 0, v[16:17]
	v_lshlrev_b64 v[2:3], 8, v[6:7]
	v_and_b32_e32 v53, 15, v0
	v_and_b32_e32 v54, 64, v0
	v_and_b32_e32 v50, 0xffffff80, v0
	v_lshl_add_u64 v[4:5], v[22:23], 0, v[2:3]
	v_or_b32_e32 v2, 16, v6
	v_or_b32_e32 v6, 32, v6
	v_or_b32_e32 v0, 48, v0
	v_ashrrev_i32_e32 v3, 31, v2
	v_ashrrev_i32_e32 v7, 31, v6
	v_ashrrev_i32_e32 v1, 31, v0
	v_lshlrev_b64 v[2:3], 8, v[2:3]
	v_lshlrev_b64 v[6:7], 8, v[6:7]
	v_lshlrev_b64 v[0:1], 8, v[0:1]
	v_lshl_add_u64 v[2:3], v[22:23], 0, v[2:3]
	v_lshl_add_u64 v[6:7], v[22:23], 0, v[6:7]
	v_lshl_add_u64 v[0:1], v[22:23], 0, v[0:1]
	global_load_dwordx4 v[138:141], v[4:5], off
	global_load_dwordx4 v[142:145], v[6:7], off
	global_load_dwordx4 v[146:149], v[2:3], off
	global_load_dwordx4 v[150:153], v[0:1], off
	global_load_dwordx4 v[154:157], v[4:5], off offset:64
	global_load_dwordx4 v[158:161], v[2:3], off offset:64
	global_load_dwordx4 v[162:165], v[6:7], off offset:64
	global_load_dwordx4 v[166:169], v[0:1], off offset:64
	global_load_dwordx4 v[170:173], v[4:5], off offset:128
	global_load_dwordx4 v[174:177], v[2:3], off offset:128
	global_load_dwordx4 v[178:181], v[6:7], off offset:128
	global_load_dwordx4 v[182:185], v[0:1], off offset:128
	global_load_dwordx4 v[186:189], v[4:5], off offset:192
	global_load_dwordx4 v[190:193], v[2:3], off offset:192
	global_load_dwordx4 v[194:197], v[6:7], off offset:192
	global_load_dwordx4 v[208:211], v[0:1], off offset:192
	s_waitcnt lgkmcnt(0)
	s_barrier
	s_waitcnt vmcnt(0)
	v_mov_b64_e32 v[8:9], v[138:139]
	v_mov_b64_e32 v[10:11], v[140:141]
	v_mov_b64_e32 v[18:19], v[142:143]
	v_mov_b64_e32 v[20:21], v[144:145]
	v_mov_b64_e32 v[12:13], v[146:147]
	v_mov_b64_e32 v[14:15], v[148:149]
	v_mov_b64_e32 v[22:23], v[150:151]
	v_mov_b64_e32 v[24:25], v[152:153]
	v_lshl_add_u32 v26, v50, 1, 0
	v_mul_u32_u24_e32 v27, 0x410, v53
	v_add3_u32 v16, v26, v16, v27
	ds_read_b128 v[26:29], v16
	ds_read_b128 v[42:45], v16 offset:16640
	ds_read_b128 v[64:67], v16 offset:33280
	ds_read_b128 v[84:87], v16 offset:49920
	v_readlane_b32 s8, v255, 37
	v_readlane_b32 s9, v255, 38
	v_ashrrev_i32_e32 v51, 31, v50
	v_lshl_or_b32 v52, v52, 2, v54
	v_or_b32_e32 v53, s18, v53
	s_waitcnt vmcnt(0) lgkmcnt(0)
	v_mfma_f32_16x16x32_bf16 v[30:33], v[8:11], v[26:29], 0
	v_mfma_f32_16x16x32_bf16 v[34:37], v[12:15], v[26:29], 0
	v_mfma_f32_16x16x32_bf16 v[38:41], v[18:21], v[26:29], 0
	v_mfma_f32_16x16x32_bf16 v[26:29], v[22:25], v[26:29], 0
	v_mfma_f32_16x16x32_bf16 v[46:49], v[8:11], v[42:45], 0
	v_mfma_f32_16x16x32_bf16 v[56:59], v[12:15], v[42:45], 0
	v_mfma_f32_16x16x32_bf16 v[60:63], v[18:21], v[42:45], 0
	v_mfma_f32_16x16x32_bf16 v[42:45], v[22:25], v[42:45], 0
	v_mfma_f32_16x16x32_bf16 v[68:71], v[8:11], v[64:67], 0
	v_mfma_f32_16x16x32_bf16 v[72:75], v[12:15], v[64:67], 0
	v_mfma_f32_16x16x32_bf16 v[80:83], v[18:21], v[64:67], 0
	v_mfma_f32_16x16x32_bf16 v[64:67], v[22:25], v[64:67], 0
	v_mfma_f32_16x16x32_bf16 v[8:11], v[8:11], v[84:87], 0
	v_mfma_f32_16x16x32_bf16 v[12:15], v[12:15], v[84:87], 0
	v_mfma_f32_16x16x32_bf16 v[18:21], v[18:21], v[84:87], 0
	v_mfma_f32_16x16x32_bf16 v[22:25], v[22:25], v[84:87], 0
	v_mov_b64_e32 v[84:85], v[154:155]
	v_mov_b64_e32 v[86:87], v[156:157]
	v_mov_b64_e32 v[88:89], v[158:159]
	v_mov_b64_e32 v[90:91], v[160:161]
	v_mov_b64_e32 v[92:93], v[162:163]
	v_mov_b64_e32 v[94:95], v[164:165]
	v_mov_b64_e32 v[96:97], v[166:167]
	v_mov_b64_e32 v[98:99], v[168:169]
	ds_read_b128 v[100:103], v16 offset:64
	s_waitcnt vmcnt(0) lgkmcnt(0)
	v_mfma_f32_16x16x32_bf16 v[30:33], v[84:87], v[100:103], v[30:33]
	v_mfma_f32_16x16x32_bf16 v[34:37], v[88:91], v[100:103], v[34:37]
	v_mfma_f32_16x16x32_bf16 v[38:41], v[92:95], v[100:103], v[38:41]
	v_mfma_f32_16x16x32_bf16 v[26:29], v[96:99], v[100:103], v[26:29]
	ds_read_b128 v[100:103], v16 offset:16704
	s_waitcnt lgkmcnt(0)
	v_mfma_f32_16x16x32_bf16 v[46:49], v[84:87], v[100:103], v[46:49]
	v_mfma_f32_16x16x32_bf16 v[56:59], v[88:91], v[100:103], v[56:59]
	v_mfma_f32_16x16x32_bf16 v[60:63], v[92:95], v[100:103], v[60:63]
	v_mfma_f32_16x16x32_bf16 v[42:45], v[96:99], v[100:103], v[42:45]
	ds_read_b128 v[100:103], v16 offset:33344
	s_waitcnt lgkmcnt(0)
	v_mfma_f32_16x16x32_bf16 v[68:71], v[84:87], v[100:103], v[68:71]
	v_mfma_f32_16x16x32_bf16 v[72:75], v[88:91], v[100:103], v[72:75]
	v_mfma_f32_16x16x32_bf16 v[80:83], v[92:95], v[100:103], v[80:83]
	v_mfma_f32_16x16x32_bf16 v[64:67], v[96:99], v[100:103], v[64:67]
	ds_read_b128 v[100:103], v16 offset:49984
	s_waitcnt lgkmcnt(0)
	v_mfma_f32_16x16x32_bf16 v[8:11], v[84:87], v[100:103], v[8:11]
	v_mfma_f32_16x16x32_bf16 v[12:15], v[88:91], v[100:103], v[12:15]
	v_mfma_f32_16x16x32_bf16 v[18:21], v[92:95], v[100:103], v[18:21]
	v_mfma_f32_16x16x32_bf16 v[22:25], v[96:99], v[100:103], v[22:25]
	v_mov_b64_e32 v[84:85], v[170:171]
	v_mov_b64_e32 v[86:87], v[172:173]
	v_mov_b64_e32 v[88:89], v[174:175]
	v_mov_b64_e32 v[90:91], v[176:177]
	v_mov_b64_e32 v[92:93], v[178:179]
	v_mov_b64_e32 v[94:95], v[180:181]
	v_mov_b64_e32 v[96:97], v[182:183]
	v_mov_b64_e32 v[98:99], v[184:185]
	ds_read_b128 v[100:103], v16 offset:128
	s_waitcnt vmcnt(0) lgkmcnt(0)
	v_mfma_f32_16x16x32_bf16 v[30:33], v[84:87], v[100:103], v[30:33]
	v_mfma_f32_16x16x32_bf16 v[34:37], v[88:91], v[100:103], v[34:37]
	v_mfma_f32_16x16x32_bf16 v[38:41], v[92:95], v[100:103], v[38:41]
	v_mfma_f32_16x16x32_bf16 v[100:103], v[96:99], v[100:103], v[26:29]
	s_nop 2
	ds_read_b128 v[26:29], v16 offset:16768
	s_waitcnt lgkmcnt(0)
	v_mfma_f32_16x16x32_bf16 v[46:49], v[84:87], v[26:29], v[46:49]
	v_mfma_f32_16x16x32_bf16 v[56:59], v[88:91], v[26:29], v[56:59]
	v_mfma_f32_16x16x32_bf16 v[60:63], v[92:95], v[26:29], v[60:63]
	v_mfma_f32_16x16x32_bf16 v[42:45], v[96:99], v[26:29], v[42:45]
	ds_read_b128 v[26:29], v16 offset:33408
	s_waitcnt lgkmcnt(0)
	v_mfma_f32_16x16x32_bf16 v[68:71], v[84:87], v[26:29], v[68:71]
	v_mfma_f32_16x16x32_bf16 v[72:75], v[88:91], v[26:29], v[72:75]
	v_mfma_f32_16x16x32_bf16 v[80:83], v[92:95], v[26:29], v[80:83]
	v_mfma_f32_16x16x32_bf16 v[64:67], v[96:99], v[26:29], v[64:67]
	ds_read_b128 v[26:29], v16 offset:50048
	s_waitcnt lgkmcnt(0)
	v_mfma_f32_16x16x32_bf16 v[18:21], v[92:95], v[26:29], v[18:21]
	v_mfma_f32_16x16x32_bf16 v[92:95], v[96:99], v[26:29], v[22:25]
	v_mov_b64_e32 v[96:97], v[186:187]
	v_mov_b64_e32 v[98:99], v[188:189]
	v_mov_b64_e32 v[104:105], v[190:191]
	v_mov_b64_e32 v[106:107], v[192:193]
	v_mov_b64_e32 v[108:109], v[194:195]
	v_mov_b64_e32 v[110:111], v[196:197]
	s_nop 0
	v_mov_b64_e32 v[0:1], v[208:209]
	v_mov_b64_e32 v[2:3], v[210:211]
	ds_read_b128 v[4:7], v16 offset:192
	v_mfma_f32_16x16x32_bf16 v[84:87], v[84:87], v[26:29], v[8:11]
	v_mfma_f32_16x16x32_bf16 v[88:91], v[88:91], v[26:29], v[12:15]
	s_waitcnt vmcnt(0) lgkmcnt(0)
	v_mfma_f32_16x16x32_bf16 v[112:115], v[96:99], v[4:7], v[30:33]
	v_mfma_f32_16x16x32_bf16 v[34:37], v[104:107], v[4:7], v[34:37]
	v_mfma_f32_16x16x32_bf16 v[26:29], v[108:111], v[4:7], v[38:41]
	v_mfma_f32_16x16x32_bf16 v[8:11], v[0:3], v[4:7], v[100:103]
	ds_read_b128 v[4:7], v16 offset:16832
	s_waitcnt lgkmcnt(0)
	v_mfma_f32_16x16x32_bf16 v[100:103], v[96:99], v[4:7], v[46:49]
	v_mfma_f32_16x16x32_bf16 v[38:41], v[104:107], v[4:7], v[56:59]
	v_mfma_f32_16x16x32_bf16 v[30:33], v[108:111], v[4:7], v[60:63]
	s_nop 1
	ds_read_b128 v[56:59], v16 offset:50112
	v_mfma_f32_16x16x32_bf16 v[12:15], v[0:3], v[4:7], v[42:45]
	ds_read_b128 v[4:7], v16 offset:33472
	s_mov_b32 s4, 0
	s_ashr_i32 s5, s4, 31
	s_lshl_b64 s[4:5], s[4:5], 3
	s_add_u32 s4, s0, s4
	s_addc_u32 s5, s1, s5
	s_load_dwordx2 s[4:5], s[4:5], 0xb8
	s_waitcnt lgkmcnt(0)
	v_mfma_f32_16x16x32_bf16 v[60:63], v[96:99], v[4:7], v[68:71]
	v_lshlrev_b32_e32 v16, 2, v52
	s_add_u32 s4, s4, s8
	s_addc_u32 s5, s5, s9
	v_mfma_f32_16x16x32_bf16 v[42:45], v[104:107], v[4:7], v[72:75]
	v_mfma_f32_16x16x32_bf16 v[22:25], v[108:111], v[4:7], v[80:83]
	v_mfma_f32_16x16x32_bf16 v[4:7], v[0:3], v[4:7], v[64:67]
	v_mfma_f32_16x16x32_bf16 v[64:67], v[96:99], v[56:59], v[84:87]
	v_mfma_f32_16x16x32_bf16 v[46:49], v[104:107], v[56:59], v[88:91]
	v_mfma_f32_16x16x32_bf16 v[18:21], v[108:111], v[56:59], v[18:21]
	v_mfma_f32_16x16x32_bf16 v[0:3], v[0:3], v[56:59], v[92:95]
	v_lshl_add_u64 v[56:57], v[50:51], 2, s[4:5]
	v_lshl_add_u64 v[54:55], v[56:57], 0, v[16:17]
	global_load_dwordx4 v[212:215], v[54:55], off
	global_load_dwordx4 v[216:219], v[54:55], off offset:64
	global_load_dwordx4 v[220:223], v[54:55], off offset:128
	global_load_dwordx4 v[224:227], v[54:55], off offset:192
	v_readlane_b32 s4, v255, 45
	v_readlane_b32 s5, v255, 46
	v_lshlrev_b32_e32 v16, 1, v52
	s_waitcnt vmcnt(0)
	v_mov_b64_e32 v[68:69], v[212:213]
	v_mov_b64_e32 v[70:71], v[214:215]
	v_mul_f32_e32 v52, v103, v71
	v_lshl_add_u64 v[50:51], v[50:51], 1, s[4:5]
	v_lshl_add_u64 v[56:57], v[50:51], 0, v[16:17]
	v_mul_f32_e32 v16, v112, v68
	v_mul_f32_e32 v50, v113, v69
	v_cvt_pk_bf16_f32 v50, v16, v50
	v_mul_f32_e32 v16, v114, v70
	v_mul_f32_e32 v51, v115, v71
	v_cvt_pk_bf16_f32 v51, v16, v51
	v_lshlrev_b32_e32 v16, 10, v53
	v_lshl_add_u64 v[58:59], v[56:57], 0, v[16:17]
	global_store_dwordx2 v[58:59], v[50:51], off
	v_mul_f32_e32 v50, v100, v68
	v_mul_f32_e32 v51, v101, v69
	v_cvt_pk_bf16_f32 v50, v50, v51
	v_mul_f32_e32 v51, v102, v70
	v_cvt_pk_bf16_f32 v51, v51, v52
	v_or_b32_e32 v52, 0x4000, v16
	v_mov_b32_e32 v53, v17
	v_lshl_add_u64 v[72:73], v[56:57], 0, v[52:53]
	global_store_dwordx2 v[72:73], v[50:51], off
	v_mul_f32_e32 v50, v60, v68
	v_mul_f32_e32 v51, v61, v69
	v_cvt_pk_bf16_f32 v60, v50, v51
	v_mul_f32_e32 v50, v62, v70
	v_mul_f32_e32 v51, v63, v71
	v_cvt_pk_bf16_f32 v61, v50, v51
	v_or_b32_e32 v50, 0x8000, v16
	v_mov_b32_e32 v51, v17
	v_lshl_add_u64 v[62:63], v[56:57], 0, v[50:51]
	global_store_dwordx2 v[62:63], v[60:61], off
	v_mul_f32_e32 v60, v64, v68
	v_mul_f32_e32 v61, v65, v69
	v_cvt_pk_bf16_f32 v60, v60, v61
	v_mul_f32_e32 v61, v66, v70
	v_mul_f32_e32 v62, v67, v71
	v_or_b32_e32 v16, 0xc000, v16
	v_cvt_pk_bf16_f32 v61, v61, v62
	v_lshl_add_u64 v[62:63], v[56:57], 0, v[16:17]
	global_store_dwordx2 v[62:63], v[60:61], off
	v_mov_b64_e32 v[60:61], v[216:217]
	v_mov_b64_e32 v[62:63], v[218:219]
	v_lshl_add_u64 v[64:65], v[56:57], 0, 32
	s_mov_b64 s[4:5], 0x60
	v_mul_f32_e32 v34, v34, v60
	v_mul_f32_e32 v35, v35, v61
	v_cvt_pk_bf16_f32 v34, v34, v35
	v_mul_f32_e32 v35, v36, v62
	v_mul_f32_e32 v36, v37, v63
	v_cvt_pk_bf16_f32 v35, v35, v36
	global_store_dwordx2 v[58:59], v[34:35], off offset:32
	v_mul_f32_e32 v34, v38, v60
	v_mul_f32_e32 v35, v39, v61
	v_cvt_pk_bf16_f32 v34, v34, v35
	v_mul_f32_e32 v35, v40, v62
	v_mul_f32_e32 v36, v41, v63
	v_cvt_pk_bf16_f32 v35, v35, v36
	v_lshl_add_u64 v[36:37], v[64:65], 0, v[52:53]
	global_store_dwordx2 v[36:37], v[34:35], off
	v_mul_f32_e32 v34, v42, v60
	v_mul_f32_e32 v35, v43, v61
	v_cvt_pk_bf16_f32 v34, v34, v35
	v_mul_f32_e32 v35, v44, v62
	v_mul_f32_e32 v36, v45, v63
	v_cvt_pk_bf16_f32 v35, v35, v36
	v_lshl_add_u64 v[36:37], v[64:65], 0, v[50:51]
	global_store_dwordx2 v[36:37], v[34:35], off
	v_mul_f32_e32 v34, v46, v60
	v_mul_f32_e32 v35, v47, v61
	v_cvt_pk_bf16_f32 v34, v34, v35
	v_mul_f32_e32 v35, v48, v62
	v_mul_f32_e32 v36, v49, v63
	v_cvt_pk_bf16_f32 v35, v35, v36
	v_lshl_add_u64 v[36:37], v[64:65], 0, v[16:17]
	global_store_dwordx2 v[36:37], v[34:35], off
	v_mov_b64_e32 v[34:35], v[220:221]
	v_mov_b64_e32 v[36:37], v[222:223]
	v_lshl_add_u64 v[38:39], v[56:57], 0, 64
	v_mul_f32_e32 v26, v26, v34
	v_mul_f32_e32 v27, v27, v35
	v_cvt_pk_bf16_f32 v26, v26, v27
	v_mul_f32_e32 v27, v28, v36
	v_mul_f32_e32 v28, v29, v37
	v_cvt_pk_bf16_f32 v27, v27, v28
	global_store_dwordx2 v[58:59], v[26:27], off offset:64
	v_mul_f32_e32 v26, v30, v34
	v_mul_f32_e32 v27, v31, v35
	v_mul_f32_e32 v22, v22, v34
	v_mul_f32_e32 v23, v23, v35
	v_mul_f32_e32 v18, v18, v34
	v_mul_f32_e32 v19, v19, v35
	v_cvt_pk_bf16_f32 v26, v26, v27
	v_mul_f32_e32 v27, v32, v36
	v_mul_f32_e32 v28, v33, v37
	v_cvt_pk_bf16_f32 v22, v22, v23
	v_mul_f32_e32 v23, v24, v36
	v_mul_f32_e32 v24, v25, v37
	v_cvt_pk_bf16_f32 v18, v18, v19
	v_mul_f32_e32 v19, v20, v36
	v_mul_f32_e32 v20, v21, v37
	v_cvt_pk_bf16_f32 v27, v27, v28
	v_lshl_add_u64 v[28:29], v[38:39], 0, v[52:53]
	v_cvt_pk_bf16_f32 v23, v23, v24
	v_lshl_add_u64 v[24:25], v[38:39], 0, v[50:51]
	v_cvt_pk_bf16_f32 v19, v19, v20
	v_lshl_add_u64 v[20:21], v[38:39], 0, v[16:17]
	global_store_dwordx2 v[28:29], v[26:27], off
	global_store_dwordx2 v[24:25], v[22:23], off
	global_store_dwordx2 v[20:21], v[18:19], off
	v_mov_b64_e32 v[18:19], v[224:225]
	v_mov_b64_e32 v[20:21], v[226:227]
	v_lshl_add_u64 v[22:23], v[56:57], 0, s[4:5]
	v_mul_f32_e32 v8, v8, v18
	v_mul_f32_e32 v9, v9, v19
	v_cvt_pk_bf16_f32 v8, v8, v9
	v_mul_f32_e32 v9, v10, v20
	v_mul_f32_e32 v10, v11, v21
	v_cvt_pk_bf16_f32 v9, v9, v10
	global_store_dwordx2 v[58:59], v[8:9], off offset:96
	v_mul_f32_e32 v8, v12, v18
	v_mul_f32_e32 v9, v13, v19
	v_mul_f32_e32 v4, v4, v18
	v_mul_f32_e32 v5, v5, v19
	v_mul_f32_e32 v0, v0, v18
	v_mul_f32_e32 v1, v1, v19
	v_cvt_pk_bf16_f32 v8, v8, v9
	v_mul_f32_e32 v9, v14, v20
	v_mul_f32_e32 v10, v15, v21
	v_cvt_pk_bf16_f32 v4, v4, v5
	v_mul_f32_e32 v5, v6, v20
	v_mul_f32_e32 v6, v7, v21
	v_cvt_pk_bf16_f32 v0, v0, v1
	v_mul_f32_e32 v1, v2, v20
	v_mul_f32_e32 v2, v3, v21
	v_cvt_pk_bf16_f32 v9, v9, v10
	v_lshl_add_u64 v[10:11], v[22:23], 0, v[52:53]
	v_cvt_pk_bf16_f32 v5, v5, v6
	v_lshl_add_u64 v[6:7], v[22:23], 0, v[50:51]
	v_cvt_pk_bf16_f32 v1, v1, v2
	v_lshl_add_u64 v[2:3], v[22:23], 0, v[16:17]
	global_store_dwordx2 v[10:11], v[8:9], off
	global_store_dwordx2 v[6:7], v[4:5], off
	global_store_dwordx2 v[2:3], v[0:1], off
	s_waitcnt lgkmcnt(0)
	s_barrier
